# grid barrier made XCD-hierarchical after the first (flat, census-completing) sync: per-XCC arrival counters, one L2 write-back per XCD by its last arriver, cross-XCC counter + generation words inside
# speedup vs baseline: 1.3649x; 1.0258x over previous
; DI void grid_barrier(unsigned* bar, unsigned& epoch) {
;   __syncthreads();
;   ++epoch;
;   if (threadIdx.x == 0) {
;     __builtin_amdgcn_fence(__ATOMIC_RELEASE, "agent");
;     asm volatile("s_waitcnt vmcnt(0)" ::: "memory");
.LBB0_625:
	v_readlane_b32 s0, v254, 10
	s_add_i32 s0, s0, 1
	s_waitcnt vmcnt(0) lgkmcnt(0)
	v_writelane_b32 v254, s0, 10
	s_barrier
	s_mov_b64 s[0:1], exec
	v_readlane_b32 s6, v252, 25
	v_readlane_b32 s7, v252, 26
	s_and_b64 s[6:7], s[0:1], s[6:7]
	s_mov_b64 exec, s[6:7]
	s_cbranch_execnz .LBB0_626
	s_getpc_b64 s[98:99]

; DI void grid_barrier(unsigned* bar, unsigned& epoch) {
;     ...
;   if (threadIdx.x == 0) {
;     __builtin_amdgcn_fence(__ATOMIC_RELEASE, "agent");
;     asm volatile("s_waitcnt vmcnt(0)" ::: "memory");
;     const unsigned target = epoch * gridDim.x;
;     __hip_atomic_fetch_add(bar, 1u, __ATOMIC_RELAXED, __HIP_MEMORY_SCOPE_AGENT);
.LBB0_626:
	v_readlane_b32 s6, v254, 10
	s_cmp_gt_u32 s6, 1
	s_cbranch_scc1 .Lmy_xbar
	s_mov_b64 s[6:7], exec
	buffer_wbl2 sc1
	s_waitcnt vmcnt(0)
	s_waitcnt vmcnt(0)
	v_mbcnt_lo_u32_b32 v0, s6, 0
	v_mbcnt_hi_u32_b32 v0, s7, v0
	v_cmp_eq_u32_e32 vcc, 0, v0
	s_and_saveexec_b64 s[8:9], vcc
	s_cbranch_execz .LBB0_628
	s_bcnt1_i32_b64 s6, s[6:7]
	v_mov_b32_e32 v0, s6
	v_readlane_b32 s6, v252, 49
	v_readlane_b32 s7, v252, 50
	s_nop 4
	global_atomic_add v199, v0, s[6:7]

; DI void grid_barrier(unsigned* bar, unsigned& epoch) {
;     ...
;     while (__hip_atomic_load(bar, __ATOMIC_RELAXED, __HIP_MEMORY_SCOPE_AGENT) < target) {
;       if (spins < 64u) __builtin_amdgcn_s_sleep(2); else __builtin_amdgcn_s_sleep(16);
;       if (++spins > (1u << 22)) break;
;     }
;     __builtin_amdgcn_fence(__ATOMIC_ACQUIRE, "agent");
;     asm volatile("s_waitcnt vmcnt(0)" ::: "memory");
;   }
.Lmy_to_67:
	s_getpc_b64 s[98:99]

; DI void grid_barrier(unsigned* bar, unsigned& epoch) {
;   __syncthreads();
;   ++epoch;
;   if (threadIdx.x == 0) {
;     __builtin_amdgcn_fence(__ATOMIC_RELEASE, "agent");
;     asm volatile("s_waitcnt vmcnt(0)" ::: "memory");
;     const unsigned target = epoch * gridDim.x;
;     __hip_atomic_fetch_add(bar, 1u, __ATOMIC_RELAXED, __HIP_MEMORY_SCOPE_AGENT);
;     unsigned spins = 0;
;     while (__hip_atomic_load(bar, __ATOMIC_RELAXED, __HIP_MEMORY_SCOPE_AGENT) < target) {
;       if (spins < 64u) __builtin_amdgcn_s_sleep(2); else __builtin_amdgcn_s_sleep(16);
;       if (++spins > (1u << 22)) break;
;     }
;     __builtin_amdgcn_fence(__ATOMIC_ACQUIRE, "agent");
;     asm volatile("s_waitcnt vmcnt(0)" ::: "memory");
;   }
;   __syncthreads();
; }
.Lmy_xbar:
	s_add_i32 s9, s6, -1
	v_readlane_b32 s10, v252, 49
	v_readlane_b32 s11, v252, 50
	s_getreg_b32 s8, hwreg(HW_REG_XCC_ID, 0, 4)
	s_and_b32 s8, s8, 7
	s_lshl_b32 s8, s8, 2
	s_nop 1
	s_add_u32 s6, s10, s8
	s_addc_u32 s7, s11, 0
	s_cmp_gt_u32 s9, 1
	s_cbranch_scc1 .Lmy_xb_have
	global_load_dword v0, v199, s[6:7] offset:64 sc1
	s_waitcnt vmcnt(0)
	s_nop 0
	v_readfirstlane_b32 s8, v0
	s_max_u32 s8, s8, 1
	s_nop 0
	v_writelane_b32 v255, s8, 40
	s_mov_b32 s98, 0
	global_load_dword v0, v199, s[10:11] offset:64 sc1
	s_waitcnt vmcnt(0)
	s_nop 0
	v_readfirstlane_b32 s99, v0
	s_cmp_lg_u32 s99, 0
	s_cselect_b32 s99, 1, 0
	s_add_i32 s98, s98, s99
	global_load_dword v0, v199, s[10:11] offset:68 sc1
	s_waitcnt vmcnt(0)
	s_nop 0
	v_readfirstlane_b32 s99, v0
	s_cmp_lg_u32 s99, 0
	s_cselect_b32 s99, 1, 0
	s_add_i32 s98, s98, s99
	global_load_dword v0, v199, s[10:11] offset:72 sc1
	s_waitcnt vmcnt(0)
	s_nop 0
	v_readfirstlane_b32 s99, v0
	s_cmp_lg_u32 s99, 0
	s_cselect_b32 s99, 1, 0
	s_add_i32 s98, s98, s99
	global_load_dword v0, v199, s[10:11] offset:76 sc1
	s_waitcnt vmcnt(0)
	s_nop 0
	v_readfirstlane_b32 s99, v0
	s_cmp_lg_u32 s99, 0
	s_cselect_b32 s99, 1, 0
	s_add_i32 s98, s98, s99
	global_load_dword v0, v199, s[10:11] offset:80 sc1
	s_waitcnt vmcnt(0)
	s_nop 0
	v_readfirstlane_b32 s99, v0
	s_cmp_lg_u32 s99, 0
	s_cselect_b32 s99, 1, 0
	s_add_i32 s98, s98, s99
	global_load_dword v0, v199, s[10:11] offset:84 sc1
	s_waitcnt vmcnt(0)
	s_nop 0
	v_readfirstlane_b32 s99, v0
	s_cmp_lg_u32 s99, 0
	s_cselect_b32 s99, 1, 0
	s_add_i32 s98, s98, s99
	global_load_dword v0, v199, s[10:11] offset:88 sc1
	s_waitcnt vmcnt(0)
	s_nop 0
	v_readfirstlane_b32 s99, v0
	s_cmp_lg_u32 s99, 0
	s_cselect_b32 s99, 1, 0
	s_add_i32 s98, s98, s99
	global_load_dword v0, v199, s[10:11] offset:92 sc1
	s_waitcnt vmcnt(0)
	s_nop 0
	v_readfirstlane_b32 s99, v0
	s_cmp_lg_u32 s99, 0
	s_cselect_b32 s99, 1, 0
	s_add_i32 s98, s98, s99
	s_max_u32 s98, s98, 1
	s_nop 0
	v_writelane_b32 v255, s98, 41
.Lmy_xb_have:
	s_nop 1
	v_readlane_b32 s8, v255, 40
	v_readlane_b32 s98, v255, 41
	v_mov_b32_e32 v0, 1
	global_atomic_add v0, v199, v0, s[6:7] offset:128 sc0
	s_waitcnt vmcnt(0)
	s_nop 0
	v_readfirstlane_b32 s99, v0
	s_add_i32 s99, s99, 1
	s_mul_i32 s8, s8, s9
	s_cmp_eq_u32 s99, s8
	s_cbranch_scc0 .Lmy_xb_wait_local
	buffer_wbl2 sc1
	s_waitcnt vmcnt(0)
	v_mov_b32_e32 v0, 1
	global_atomic_add v0, v199, v0, s[10:11] offset:192 sc0
	s_waitcnt vmcnt(0)
	s_nop 0
	v_readfirstlane_b32 s99, v0
	s_add_i32 s99, s99, 1
	s_mul_i32 s8, s98, s9
	s_cmp_eq_u32 s99, s8
	s_cbranch_scc0 .Lmy_xb_wait_top
	v_mov_b32_e32 v0, 1
	global_atomic_add v199, v0, s[10:11] offset:196
	s_branch .Lmy_xb_release
.Lmy_xb_wait_top:
	s_mov_b32 s8, 0
.Lmy_xb_top_loop:
	global_load_dword v0, v199, s[10:11] offset:196 sc1
	s_waitcnt vmcnt(0)
	v_cmp_le_u32_e32 vcc, s9, v0
	s_cbranch_vccnz .Lmy_xb_release
	s_cmp_lt_u32 s8, 64
	s_cbranch_scc1 .Lmy_xb_top_fast
	s_sleep 16
.Lmy_xb_top_fast:
	s_sleep 2
	s_add_i32 s8, s8, 1
	s_cmp_lt_u32 s8, 0x100000
	s_cbranch_scc1 .Lmy_xb_top_loop
.Lmy_xb_release:
	v_mov_b32_e32 v0, 1
	global_atomic_add v199, v0, s[6:7] offset:160
	s_branch .Lmy_to_67

; DI void grid_barrier(unsigned* bar, unsigned& epoch) {
;     ...
;     unsigned spins = 0;
;     while (__hip_atomic_load(bar, __ATOMIC_RELAXED, __HIP_MEMORY_SCOPE_AGENT) < target) {
;       if (spins < 64u) __builtin_amdgcn_s_sleep(2); else __builtin_amdgcn_s_sleep(16);
;       if (++spins > (1u << 22)) break;
;     }
.Lmy_xb_loc_loop:
	global_load_dword v0, v199, s[6:7] offset:160 sc1
	s_waitcnt vmcnt(0)
	v_cmp_le_u32_e32 vcc, s9, v0
	s_cbranch_vccnz .Lmy_to_67
	s_cmp_lt_u32 s8, 64
	s_cbranch_scc1 .Lmy_xb_loc_fast
	s_sleep 16
.Lmy_xb_loc_fast:
	s_sleep 2
	s_add_i32 s8, s8, 1
	s_cmp_lt_u32 s8, 0x100000
	s_cbranch_scc1 .Lmy_xb_loc_loop
	s_branch .Lmy_to_67
